# P8: half the workgroups (blockIdx bit 3) run the w_d conversion before their GEMM units instead of after, so the memory-bound conversion overlaps the other half's K-loops
# baseline (speedup 1.0000x reference)
.LBB0_1042:
	s_load_dwordx2 s[2:3], s[0:1], 0xd8
	s_waitcnt lgkmcnt(0)
	s_cmp_lt_i32 s2, 9
	s_cselect_b64 s[4:5], -1, 0
	s_and_b64 s[2:3], s[4:5], s[6:7]
	s_andn2_b64 vcc, exec, s[2:3]
	s_cbranch_vccnz .LBB0_1086
	s_bitcmp0_b32 s96, 3
	s_cbranch_scc1 .Lcvte_done
	s_cmpk_gt_i32 s96, 0x2bf
	s_cbranch_scc1 .Lcvte_done
	s_mul_hi_i32 s2, s96, 0x2e8ba2e9
	v_mov_b32_e32 v50, v184
	s_lshr_b32 s3, s2, 31
	s_ashr_i32 s2, s2, 3
	s_add_i32 s2, s2, s3
	v_and_b32_e32 v2, 0x7f, v50
	s_load_dwordx2 s[6:7], s[0:1], 0xb8
	v_lshl_or_b32 v0, s2, 7, v2
	s_mul_i32 s2, s2, 44
	v_ashrrev_i32_e32 v3, 7, v50
	s_sub_i32 s2, s96, s2
	s_waitcnt vmcnt(0)
	v_lshl_add_u32 v4, s2, 7, v3
	v_ashrrev_i32_e32 v5, 31, v4
	v_lshlrev_b64 v[4:5], 13, v[4:5]
	s_waitcnt lgkmcnt(0)
	v_lshl_add_u64 v[4:5], s[6:7], 0, v[4:5]
	v_ashrrev_i32_e32 v1, 31, v0
	v_lshl_add_u64 v[0:1], v[0:1], 2, v[4:5]
	s_mov_b32 s2, 0x8000
	v_add_co_u32_e32 v12, vcc, s2, v0
	s_mov_b32 s3, 0x10000
	s_nop 0
	v_addc_co_u32_e32 v13, vcc, 0, v1, vcc
	v_add_co_u32_e32 v14, vcc, s3, v0
	s_mov_b32 s10, 0x18000
	s_nop 0
	v_addc_co_u32_e32 v15, vcc, 0, v1, vcc
	v_add_co_u32_e32 v16, vcc, s10, v0
	s_mov_b32 s11, 0x20000
	s_nop 0
	v_addc_co_u32_e32 v17, vcc, 0, v1, vcc
	v_add_co_u32_e32 v18, vcc, s11, v0
	s_mov_b32 s12, 0x28000
	s_nop 0
	v_addc_co_u32_e32 v19, vcc, 0, v1, vcc
	v_add_co_u32_e32 v20, vcc, s12, v0
	s_mov_b32 s13, 0x30000
	s_nop 0
	v_addc_co_u32_e32 v21, vcc, 0, v1, vcc
	v_add_co_u32_e32 v22, vcc, s13, v0
	s_mov_b32 s14, 0x38000
	s_nop 0
	v_addc_co_u32_e32 v23, vcc, 0, v1, vcc
	v_add_co_u32_e32 v24, vcc, s14, v0
	s_mov_b32 s15, 0x40000
	s_nop 0
	v_addc_co_u32_e32 v25, vcc, 0, v1, vcc
	global_load_dword v4, v[0:1], off nt
	global_load_dword v5, v[12:13], off nt
	global_load_dword v6, v[14:15], off nt
	global_load_dword v7, v[16:17], off nt
	global_load_dword v8, v[18:19], off nt
	global_load_dword v9, v[20:21], off nt
	global_load_dword v10, v[22:23], off nt
	global_load_dword v11, v[24:25], off nt
	v_add_co_u32_e32 v20, vcc, s15, v0
	s_mov_b32 s16, 0x48000
	s_nop 0
	v_addc_co_u32_e32 v21, vcc, 0, v1, vcc
	v_add_co_u32_e32 v22, vcc, s16, v0
	s_mov_b32 s17, 0x50000
	s_nop 0
	v_addc_co_u32_e32 v23, vcc, 0, v1, vcc
	v_add_co_u32_e32 v24, vcc, s17, v0
	s_mov_b32 s18, 0x58000
	s_nop 0
	v_addc_co_u32_e32 v25, vcc, 0, v1, vcc
	v_add_co_u32_e32 v26, vcc, s18, v0
	s_mov_b32 s19, 0x60000
	s_nop 0
	v_addc_co_u32_e32 v27, vcc, 0, v1, vcc
	v_add_co_u32_e32 v28, vcc, s19, v0
	s_mov_b32 s20, 0x68000
	s_nop 0
	v_addc_co_u32_e32 v29, vcc, 0, v1, vcc
	v_add_co_u32_e32 v30, vcc, s20, v0
	s_mov_b32 s21, 0x70000
	s_nop 0
	v_addc_co_u32_e32 v31, vcc, 0, v1, vcc
	v_add_co_u32_e32 v32, vcc, s21, v0
	s_mov_b32 s22, 0x78000
	s_nop 0
	v_addc_co_u32_e32 v33, vcc, 0, v1, vcc
	v_add_co_u32_e32 v34, vcc, s22, v0
	s_mov_b32 s23, 0x80000
	s_nop 0
	v_addc_co_u32_e32 v35, vcc, 0, v1, vcc
	global_load_dword v12, v[20:21], off nt
	global_load_dword v13, v[22:23], off nt
	global_load_dword v14, v[24:25], off nt
	global_load_dword v15, v[26:27], off nt
	global_load_dword v16, v[28:29], off nt
	global_load_dword v17, v[30:31], off nt
	global_load_dword v18, v[32:33], off nt
	global_load_dword v19, v[34:35], off nt
	v_add_co_u32_e32 v20, vcc, s23, v0
	s_mov_b32 s24, 0x88000
	s_nop 0
	v_addc_co_u32_e32 v21, vcc, 0, v1, vcc
	v_add_co_u32_e32 v22, vcc, s24, v0
	s_mov_b32 s25, 0x90000
	s_nop 0
	v_addc_co_u32_e32 v23, vcc, 0, v1, vcc
	v_add_co_u32_e32 v24, vcc, s25, v0
	s_mov_b32 s26, 0x98000
	s_nop 0
	v_addc_co_u32_e32 v25, vcc, 0, v1, vcc
	v_add_co_u32_e32 v26, vcc, s26, v0
	s_mov_b32 s27, 0xa0000
	s_nop 0
	v_addc_co_u32_e32 v27, vcc, 0, v1, vcc
	v_add_co_u32_e32 v28, vcc, s27, v0
	s_mov_b32 s28, 0xa8000
	s_nop 0
	v_addc_co_u32_e32 v29, vcc, 0, v1, vcc
	v_add_co_u32_e32 v38, vcc, s28, v0
	s_mov_b32 s29, 0xb0000
	s_nop 0
	v_addc_co_u32_e32 v39, vcc, 0, v1, vcc
	v_add_co_u32_e32 v40, vcc, s29, v0
	s_mov_b32 s30, 0xb8000
	s_nop 0
	v_addc_co_u32_e32 v41, vcc, 0, v1, vcc
	v_add_co_u32_e32 v42, vcc, s30, v0
	s_mov_b32 s31, 0xc0000
	s_nop 0
	v_addc_co_u32_e32 v43, vcc, 0, v1, vcc
	global_load_dword v30, v[20:21], off nt
	global_load_dword v31, v[22:23], off nt
	global_load_dword v32, v[24:25], off nt
	global_load_dword v33, v[26:27], off nt
	global_load_dword v34, v[28:29], off nt
	global_load_dword v35, v[38:39], off nt
	global_load_dword v36, v[40:41], off nt
	global_load_dword v37, v[42:43], off nt
	v_add_co_u32_e32 v20, vcc, s31, v0
	s_mov_b32 s33, 0xc8000
	s_nop 0
	v_addc_co_u32_e32 v21, vcc, 0, v1, vcc
	v_add_co_u32_e32 v22, vcc, s33, v0
	s_mov_b32 s38, 0xd0000
	s_nop 0
	v_addc_co_u32_e32 v23, vcc, 0, v1, vcc
	v_add_co_u32_e32 v24, vcc, s38, v0
	s_mov_b32 s39, 0xd8000
	s_nop 0
	v_addc_co_u32_e32 v25, vcc, 0, v1, vcc
	v_add_co_u32_e32 v26, vcc, s39, v0
	s_mov_b32 s8, 0xe0000
	s_nop 0
	v_addc_co_u32_e32 v27, vcc, 0, v1, vcc
	v_add_co_u32_e32 v28, vcc, s8, v0
	s_mov_b32 s8, 0xe8000
	s_nop 0
	v_addc_co_u32_e32 v29, vcc, 0, v1, vcc
	v_add_co_u32_e32 v46, vcc, s8, v0
	s_mov_b32 s8, 0xf0000
	s_nop 0
	v_addc_co_u32_e32 v47, vcc, 0, v1, vcc
	v_add_co_u32_e32 v48, vcc, s8, v0
	s_mov_b32 s8, 0xf8000
	s_nop 0
	v_addc_co_u32_e32 v49, vcc, 0, v1, vcc
	v_add_co_u32_e32 v0, vcc, s8, v0
	s_movk_i32 s8, 0x110
	s_nop 0
	v_addc_co_u32_e32 v1, vcc, 0, v1, vcc
	global_load_dword v38, v[20:21], off nt
	global_load_dword v39, v[22:23], off nt
	global_load_dword v40, v[24:25], off nt
	global_load_dword v41, v[26:27], off nt
	global_load_dword v42, v[28:29], off nt
	global_load_dword v43, v[46:47], off nt
	global_load_dword v44, v[48:49], off nt
	global_load_dword v45, v[0:1], off nt
	v_lshlrev_b32_e32 v0, 3, v50
	v_add_u32_e32 v22, 0x200, v50
	v_add_u32_e32 v24, 0x400, v50
	v_add_u32_e32 v26, 0x600, v50
	v_and_b32_e32 v0, 0x78, v0
	v_ashrrev_i32_e32 v20, 4, v50
	v_ashrrev_i32_e32 v22, 4, v22
	v_ashrrev_i32_e32 v24, 4, v24
	v_ashrrev_i32_e32 v26, 4, v26
	s_lshl_b32 s46, s42, 7
	s_mov_b32 s40, 0
	v_mov_b32_e32 v1, 0
	v_mul_lo_u32 v21, v20, s8
	v_mul_lo_u32 v23, v22, s8
	v_mul_lo_u32 v25, v24, s8
	v_mul_lo_u32 v27, v26, s8
	v_mul_u32_u24_e32 v28, 0x110, v2
	s_lshl_b32 s41, s96, 7
	v_add_u32_e32 v29, s46, v3
	s_movk_i32 s47, 0x7fff
	v_lshlrev_b32_e32 v0, 1, v0
	s_movk_i32 s48, 0x2c00
	s_mov_b32 s49, s96
	s_barrier
	s_branch .Lcvte_1081

.Lcvte_done:
	s_add_u32 s3, s36, 0xe400000
	s_addc_u32 s33, s37, 0
	s_add_u32 s38, s36, 0x1bd3c000
	s_addc_u32 s39, s37, 0
	s_add_u32 s6, s36, 0x11400000
	s_addc_u32 s7, s37, 0
	s_cmpk_lg_i32 s42, 0x100
	s_mov_b64 s[8:9], -1
	s_cbranch_scc0 .LBB0_1057
	s_waitcnt vmcnt(0)
	v_mov_b32_e32 v10, v184
	s_cmpk_gt_i32 s96, 0x83f
	v_readfirstlane_b32 s2, v10
	s_cbranch_scc1 .LBB0_1056
	v_lshlrev_b32_e32 v0, 4, v10
	v_add_u32_e32 v1, 0x2000, v0
	v_ashrrev_i32_e32 v2, 31, v1
	v_lshrrev_b32_e32 v2, 22, v2
	v_add_u32_e32 v2, v1, v2
	v_ashrrev_i32_e32 v8, 10, v2
	v_mul_i32_i24_e32 v2, 0x400, v8
	v_sub_u32_e32 v1, v1, v2
	v_lshrrev_b32_e32 v2, 4, v1
	v_bitop3_b32 v1, v2, v1, 32 bitop3:0x6c
	v_ashrrev_i32_e32 v2, 31, v1
	v_lshrrev_b32_e32 v2, 26, v2
	v_add_u32_e32 v2, v1, v2
	v_lshlrev_b32_e32 v3, 3, v8
	v_ashrrev_i32_e32 v9, 6, v2
	v_and_b32_e32 v3, -16, v3
	v_add_u32_e32 v3, v9, v3
	v_and_b32_e32 v4, 3, v9
	s_mov_b32 s8, 0xfffe0
	v_lshrrev_b32_e32 v5, 2, v3
	v_lshlrev_b32_e32 v6, 1, v3
	v_and_b32_e32 v2, 0xc0, v2
	v_and_or_b32 v4, v3, s8, v4
	v_and_b32_e32 v5, 4, v5
	v_and_b32_e32 v6, 24, v6
	v_sub_u32_e32 v1, v1, v2
	v_mov_b32_e32 v2, 1
	v_or3_b32 v4, v4, v5, v6
	v_lshlrev_b32_e32 v5, 5, v8
	v_ashrrev_i16_sdwa v1, v2, sext(v1) dst_sel:DWORD dst_unused:UNUSED_PAD src0_sel:DWORD src1_sel:BYTE_0
	v_and_b32_e32 v5, 32, v5
	v_bfe_i32 v11, v1, 0, 16
	v_add_lshl_u32 v1, v5, v11, 1
	v_lshl_add_u32 v128, v4, 12, v1
	v_lshl_add_u32 v130, v3, 12, v1
	v_bfe_i32 v1, v10, 27, 1
	v_lshrrev_b32_e32 v1, 22, v1
	v_add_u32_e32 v1, v0, v1
	v_and_b32_e32 v1, 0xfffffc00, v1
	v_sub_u32_e32 v0, v0, v1
	v_lshrrev_b32_e32 v1, 4, v0
	v_ashrrev_i32_e32 v3, 31, v10
	v_bitop3_b32 v0, v1, v0, 32 bitop3:0x6c
	v_lshrrev_b32_e32 v3, 26, v3
	v_ashrrev_i32_e32 v1, 31, v0
	v_add_u32_e32 v3, v10, v3
	v_lshrrev_b32_e32 v1, 26, v1
	v_ashrrev_i32_e32 v13, 6, v3
	v_add_u32_e32 v1, v0, v1
	v_lshlrev_b32_e32 v3, 3, v13
	v_ashrrev_i32_e32 v12, 6, v1
	v_and_b32_e32 v3, -16, v3
	v_add_u32_e32 v3, v12, v3
	v_and_b32_e32 v4, 3, v12
	s_ashr_i32 s31, s96, 31
	v_and_or_b32 v4, v3, s8, v4
	s_lshr_b32 s8, s31, 29
	s_add_i32 s8, s96, s8
	s_ashr_i32 s10, s2, 6
	s_ashr_i32 s9, s8, 3
	s_and_b32 s8, s8, -8
	s_ashr_i32 s12, s2, 8
	s_lshl_b32 s30, s10, 10
	s_sub_i32 s8, s96, s8
	s_cmp_lt_i32 s8, 0
	s_movk_i32 s40, 0x109
	s_cselect_b32 s11, s40, 0x108
	s_mul_i32 s8, s8, s11
	s_add_i32 s8, s8, s9
	s_mul_hi_i32 s9, s8, 0x2e8ba2e9
	s_lshr_b32 s11, s9, 31
	s_ashr_i32 s9, s9, 5
	s_add_i32 s9, s9, s11
	s_lshl_b32 s11, s9, 2
	s_mulk_i32 s9, 0xb0
	s_sub_i32 s9, s8, s9
	s_bfe_u32 s8, s9, 0x2001d
	s_add_i32 s13, s9, s8
	s_sext_i32_i16 s8, s13
	s_and_b32 s13, s13, 0xfffc
	s_sub_i32 s9, s9, s13
	s_sext_i32_i16 s9, s9
	v_lshrrev_b32_e32 v5, 2, v3
	v_lshlrev_b32_e32 v6, 1, v3
	v_and_b32_e32 v1, 0xc0, v1
	s_lshr_b32 s8, s8, 2
	s_add_i32 s22, s11, s9
	v_and_b32_e32 v5, 4, v5
	v_and_b32_e32 v6, 24, v6
	v_sub_u32_e32 v0, v0, v1
	s_ashr_i32 s23, s22, 31
	s_bfe_i64 s[16:17], s[8:9], 0x100000
	v_or3_b32 v4, v4, v5, v6
	v_lshlrev_b32_e32 v5, 5, v13
	v_ashrrev_i16_sdwa v0, v2, sext(v0) dst_sel:DWORD dst_unused:UNUSED_PAD src0_sel:DWORD src1_sel:BYTE_0
	s_lshl_b64 s[14:15], s[22:23], 20
	s_lshl_b64 s[16:17], s[16:17], 20
	v_and_b32_e32 v5, 32, v5
	v_bfe_i32 v14, v0, 0, 16
	s_add_u32 s26, s38, s16
	v_add_lshl_u32 v0, v5, v14, 1
	s_addc_u32 s27, s39, s17
	s_add_i32 s41, s30, 0
	v_lshl_add_u32 v132, v4, 12, v0
	s_add_i32 m0, s41, 0x10000
	v_lshl_add_u32 v134, v3, 12, v0
	global_load_lds_dwordx4 v132, s[26:27]
	s_add_i32 m0, s41, 0x12000
	s_add_u32 s24, s3, s14
	global_load_lds_dwordx4 v128, s[26:27]
	s_addc_u32 s25, s33, s15
	s_mov_b32 m0, s41
	s_add_i32 s46, s41, 0x2000
	global_load_lds_dwordx4 v134, s[24:25]
	s_mov_b32 m0, s46
	s_add_u32 s14, s26, 0x80000
	global_load_lds_dwordx4 v130, s[24:25]
	s_addc_u32 s15, s27, 0
	s_add_i32 m0, s41, 0x14000
	v_mov_b32_e32 v137, 0
	global_load_lds_dwordx4 v132, s[14:15]
	s_add_i32 m0, s41, 0x16000
	v_mov_b32_e32 v133, v137
	global_load_lds_dwordx4 v128, s[14:15]
	s_add_u32 s14, s24, 0x80000
	s_addc_u32 s15, s25, 0
	s_add_i32 s47, s41, 0x4000
	s_mov_b32 m0, s47
	s_add_i32 s48, s41, 0x6000
	global_load_lds_dwordx4 v134, s[14:15]
	s_mov_b32 m0, s48
	v_mov_b32_e32 v129, v137
	global_load_lds_dwordx4 v130, s[14:15]
	v_mov_b32_e32 v135, v137
	v_mov_b32_e32 v131, v137
	s_mov_b32 s9, 0
	v_lshl_add_u64 v[6:7], s[26:27], 0, v[132:133]
	v_lshl_add_u64 v[4:5], s[26:27], 0, v[128:129]
	v_lshl_add_u64 v[2:3], s[24:25], 0, v[134:135]
	s_cmp_lg_u32 s12, 1
	v_lshl_add_u64 v[0:1], s[24:25], 0, v[130:131]
	s_cbranch_scc1 .LBB0_1047
	s_barrier

.LBB0_1078:
	s_bitcmp1_b32 s96, 3
	s_cbranch_scc1 .LBB0_1086
	s_cmpk_gt_i32 s96, 0x2bf
	s_cbranch_scc1 .LBB0_1086
	s_mul_hi_i32 s2, s96, 0x2e8ba2e9
	v_mov_b32_e32 v50, v184
	s_lshr_b32 s3, s2, 31
	s_ashr_i32 s2, s2, 3
	s_add_i32 s2, s2, s3
	v_and_b32_e32 v2, 0x7f, v50
	s_load_dwordx2 s[6:7], s[0:1], 0xb8
	v_lshl_or_b32 v0, s2, 7, v2
	s_mul_i32 s2, s2, 44
	v_ashrrev_i32_e32 v3, 7, v50
	s_sub_i32 s2, s96, s2
	s_waitcnt vmcnt(0)
	v_lshl_add_u32 v4, s2, 7, v3
	v_ashrrev_i32_e32 v5, 31, v4
	v_lshlrev_b64 v[4:5], 13, v[4:5]
	s_waitcnt lgkmcnt(0)
	v_lshl_add_u64 v[4:5], s[6:7], 0, v[4:5]
	v_ashrrev_i32_e32 v1, 31, v0
	v_lshl_add_u64 v[0:1], v[0:1], 2, v[4:5]
	s_mov_b32 s2, 0x8000
	v_add_co_u32_e32 v12, vcc, s2, v0
	s_mov_b32 s3, 0x10000
	s_nop 0
	v_addc_co_u32_e32 v13, vcc, 0, v1, vcc
	v_add_co_u32_e32 v14, vcc, s3, v0
	s_mov_b32 s10, 0x18000
	s_nop 0
	v_addc_co_u32_e32 v15, vcc, 0, v1, vcc
	v_add_co_u32_e32 v16, vcc, s10, v0
	s_mov_b32 s11, 0x20000
	s_nop 0
	v_addc_co_u32_e32 v17, vcc, 0, v1, vcc
	v_add_co_u32_e32 v18, vcc, s11, v0
	s_mov_b32 s12, 0x28000
	s_nop 0
	v_addc_co_u32_e32 v19, vcc, 0, v1, vcc
	v_add_co_u32_e32 v20, vcc, s12, v0
	s_mov_b32 s13, 0x30000
	s_nop 0
	v_addc_co_u32_e32 v21, vcc, 0, v1, vcc
	v_add_co_u32_e32 v22, vcc, s13, v0
	s_mov_b32 s14, 0x38000
	s_nop 0
	v_addc_co_u32_e32 v23, vcc, 0, v1, vcc
	v_add_co_u32_e32 v24, vcc, s14, v0
	s_mov_b32 s15, 0x40000
	s_nop 0
	v_addc_co_u32_e32 v25, vcc, 0, v1, vcc
	global_load_dword v4, v[0:1], off nt
	global_load_dword v5, v[12:13], off nt
	global_load_dword v6, v[14:15], off nt
	global_load_dword v7, v[16:17], off nt
	global_load_dword v8, v[18:19], off nt
	global_load_dword v9, v[20:21], off nt
	global_load_dword v10, v[22:23], off nt
	global_load_dword v11, v[24:25], off nt
	v_add_co_u32_e32 v20, vcc, s15, v0
	s_mov_b32 s16, 0x48000
	s_nop 0
	v_addc_co_u32_e32 v21, vcc, 0, v1, vcc
	v_add_co_u32_e32 v22, vcc, s16, v0
	s_mov_b32 s17, 0x50000
	s_nop 0
	v_addc_co_u32_e32 v23, vcc, 0, v1, vcc
	v_add_co_u32_e32 v24, vcc, s17, v0
	s_mov_b32 s18, 0x58000
	s_nop 0
	v_addc_co_u32_e32 v25, vcc, 0, v1, vcc
	v_add_co_u32_e32 v26, vcc, s18, v0
	s_mov_b32 s19, 0x60000
	s_nop 0
	v_addc_co_u32_e32 v27, vcc, 0, v1, vcc
	v_add_co_u32_e32 v28, vcc, s19, v0
	s_mov_b32 s20, 0x68000
	s_nop 0
	v_addc_co_u32_e32 v29, vcc, 0, v1, vcc
	v_add_co_u32_e32 v30, vcc, s20, v0
	s_mov_b32 s21, 0x70000
	s_nop 0
	v_addc_co_u32_e32 v31, vcc, 0, v1, vcc
	v_add_co_u32_e32 v32, vcc, s21, v0
	s_mov_b32 s22, 0x78000
	s_nop 0
	v_addc_co_u32_e32 v33, vcc, 0, v1, vcc
	v_add_co_u32_e32 v34, vcc, s22, v0
	s_mov_b32 s23, 0x80000
	s_nop 0
	v_addc_co_u32_e32 v35, vcc, 0, v1, vcc
	global_load_dword v12, v[20:21], off nt
	global_load_dword v13, v[22:23], off nt
	global_load_dword v14, v[24:25], off nt
	global_load_dword v15, v[26:27], off nt
	global_load_dword v16, v[28:29], off nt
	global_load_dword v17, v[30:31], off nt
	global_load_dword v18, v[32:33], off nt
	global_load_dword v19, v[34:35], off nt
	v_add_co_u32_e32 v20, vcc, s23, v0
	s_mov_b32 s24, 0x88000
	s_nop 0
	v_addc_co_u32_e32 v21, vcc, 0, v1, vcc
	v_add_co_u32_e32 v22, vcc, s24, v0
	s_mov_b32 s25, 0x90000
	s_nop 0
	v_addc_co_u32_e32 v23, vcc, 0, v1, vcc
	v_add_co_u32_e32 v24, vcc, s25, v0
	s_mov_b32 s26, 0x98000
	s_nop 0
	v_addc_co_u32_e32 v25, vcc, 0, v1, vcc
	v_add_co_u32_e32 v26, vcc, s26, v0
	s_mov_b32 s27, 0xa0000
	s_nop 0
	v_addc_co_u32_e32 v27, vcc, 0, v1, vcc
	v_add_co_u32_e32 v28, vcc, s27, v0
	s_mov_b32 s28, 0xa8000
	s_nop 0
	v_addc_co_u32_e32 v29, vcc, 0, v1, vcc
	v_add_co_u32_e32 v38, vcc, s28, v0
	s_mov_b32 s29, 0xb0000
	s_nop 0
	v_addc_co_u32_e32 v39, vcc, 0, v1, vcc
	v_add_co_u32_e32 v40, vcc, s29, v0
	s_mov_b32 s30, 0xb8000
	s_nop 0
	v_addc_co_u32_e32 v41, vcc, 0, v1, vcc
	v_add_co_u32_e32 v42, vcc, s30, v0
	s_mov_b32 s31, 0xc0000
	s_nop 0
	v_addc_co_u32_e32 v43, vcc, 0, v1, vcc
	global_load_dword v30, v[20:21], off nt
	global_load_dword v31, v[22:23], off nt
	global_load_dword v32, v[24:25], off nt
	global_load_dword v33, v[26:27], off nt
	global_load_dword v34, v[28:29], off nt
	global_load_dword v35, v[38:39], off nt
	global_load_dword v36, v[40:41], off nt
	global_load_dword v37, v[42:43], off nt
	v_add_co_u32_e32 v20, vcc, s31, v0
	s_mov_b32 s33, 0xc8000
	s_nop 0
	v_addc_co_u32_e32 v21, vcc, 0, v1, vcc
	v_add_co_u32_e32 v22, vcc, s33, v0
	s_mov_b32 s38, 0xd0000
	s_nop 0
	v_addc_co_u32_e32 v23, vcc, 0, v1, vcc
	v_add_co_u32_e32 v24, vcc, s38, v0
	s_mov_b32 s39, 0xd8000
	s_nop 0
	v_addc_co_u32_e32 v25, vcc, 0, v1, vcc
	v_add_co_u32_e32 v26, vcc, s39, v0
	s_mov_b32 s8, 0xe0000
	s_nop 0
	v_addc_co_u32_e32 v27, vcc, 0, v1, vcc
	v_add_co_u32_e32 v28, vcc, s8, v0
	s_mov_b32 s8, 0xe8000
	s_nop 0
	v_addc_co_u32_e32 v29, vcc, 0, v1, vcc
	v_add_co_u32_e32 v46, vcc, s8, v0
	s_mov_b32 s8, 0xf0000
	s_nop 0
	v_addc_co_u32_e32 v47, vcc, 0, v1, vcc
	v_add_co_u32_e32 v48, vcc, s8, v0
	s_mov_b32 s8, 0xf8000
	s_nop 0
	v_addc_co_u32_e32 v49, vcc, 0, v1, vcc
	v_add_co_u32_e32 v0, vcc, s8, v0
	s_movk_i32 s8, 0x110
	s_nop 0
	v_addc_co_u32_e32 v1, vcc, 0, v1, vcc
	global_load_dword v38, v[20:21], off nt
	global_load_dword v39, v[22:23], off nt
	global_load_dword v40, v[24:25], off nt
	global_load_dword v41, v[26:27], off nt
	global_load_dword v42, v[28:29], off nt
	global_load_dword v43, v[46:47], off nt
	global_load_dword v44, v[48:49], off nt
	global_load_dword v45, v[0:1], off nt
	v_lshlrev_b32_e32 v0, 3, v50
	v_add_u32_e32 v22, 0x200, v50
	v_add_u32_e32 v24, 0x400, v50
	v_add_u32_e32 v26, 0x600, v50
	v_and_b32_e32 v0, 0x78, v0
	v_ashrrev_i32_e32 v20, 4, v50
	v_ashrrev_i32_e32 v22, 4, v22
	v_ashrrev_i32_e32 v24, 4, v24
	v_ashrrev_i32_e32 v26, 4, v26
	s_lshl_b32 s46, s42, 7
	s_mov_b32 s40, 0
	v_mov_b32_e32 v1, 0
	v_mul_lo_u32 v21, v20, s8
	v_mul_lo_u32 v23, v22, s8
	v_mul_lo_u32 v25, v24, s8
	v_mul_lo_u32 v27, v26, s8
	v_mul_u32_u24_e32 v28, 0x110, v2
	s_lshl_b32 s41, s96, 7
	v_add_u32_e32 v29, s46, v3
	s_movk_i32 s47, 0x7fff
	v_lshlrev_b32_e32 v0, 1, v0
	s_movk_i32 s48, 0x2c00
	s_mov_b32 s49, s96
	s_barrier
	s_branch .LBB0_1081
